# v13 with the eight Epi2 row sum-of-squares f32 atomics issued at sc1 (system) scope: same arithmetic, stronger cross-XCD coherence for the sample rows whose four column tiles now run on four XCDs
# baseline (speedup 1.0000x reference)
.LBB0_639:
	v_pk_mul_f32 v[126:127], v[126:127], v[126:127]
	v_pk_mul_f32 v[124:125], v[124:125], v[124:125]
	v_pk_fma_f32 v[130:131], v[130:131], v[130:131], v[126:127]
	v_pk_fma_f32 v[128:129], v[128:129], v[128:129], v[124:125]
	v_cvt_pk_bf16_f32 v124, v120, v121
	v_cvt_pk_bf16_f32 v125, v122, v123
	v_pk_fma_f32 v[122:123], v[122:123], v[122:123], v[130:131]
	v_pk_fma_f32 v[120:121], v[120:121], v[120:121], v[128:129]
	v_cvt_pk_bf16_f32 v126, v116, v117
	v_cvt_pk_bf16_f32 v127, v118, v119
	v_pk_fma_f32 v[118:119], v[118:119], v[118:119], v[122:123]
	v_pk_fma_f32 v[116:117], v[116:117], v[116:117], v[120:121]
	v_lshlrev_b64 v[150:151], 1, v[150:151]
	v_add_f32_e32 v116, v116, v117
	v_add_f32_e32 v117, v118, v119
	v_add_f32_e32 v116, v116, v117
	v_mov_b32_e32 v117, v116
	s_nop 1
	v_permlane16_swap_b32_e32 v116, v117
	v_add_f32_e32 v116, v116, v117
	v_or_b32_e32 v150, 0x100, v150
	v_mov_b32_e32 v117, v116
	v_lshl_add_u64 v[150:151], s[10:11], 0, v[150:151]
	s_nop 0
	v_permlane32_swap_b32_e32 v116, v117
	global_store_dwordx4 v[150:151], v[124:127], off
	s_and_saveexec_b64 s[26:27], s[0:1]
	s_cbranch_execz .LBB0_641
	v_lshl_add_u64 v[118:119], v[148:149], 2, s[12:13]
	v_add_f32_e32 v116, v116, v117
	global_atomic_add_f32 v[118:119], v116, off sc1

.LBB0_645:
	v_pk_mul_f32 v[110:111], v[110:111], v[110:111]
	v_pk_mul_f32 v[108:109], v[108:109], v[108:109]
	v_pk_fma_f32 v[114:115], v[114:115], v[114:115], v[110:111]
	v_pk_fma_f32 v[112:113], v[112:113], v[112:113], v[108:109]
	v_cvt_pk_bf16_f32 v108, v104, v105
	v_cvt_pk_bf16_f32 v109, v106, v107
	v_pk_fma_f32 v[106:107], v[106:107], v[106:107], v[114:115]
	v_pk_fma_f32 v[104:105], v[104:105], v[104:105], v[112:113]
	v_cvt_pk_bf16_f32 v110, v100, v101
	v_cvt_pk_bf16_f32 v111, v102, v103
	v_pk_fma_f32 v[102:103], v[102:103], v[102:103], v[106:107]
	v_pk_fma_f32 v[100:101], v[100:101], v[100:101], v[104:105]
	v_lshlrev_b64 v[118:119], 1, v[118:119]
	v_add_f32_e32 v100, v100, v101
	v_add_f32_e32 v101, v102, v103
	v_add_f32_e32 v100, v100, v101
	v_mov_b32_e32 v101, v100
	s_nop 1
	v_permlane16_swap_b32_e32 v100, v101
	v_add_f32_e32 v100, v100, v101
	v_or_b32_e32 v118, 0x100, v118
	v_mov_b32_e32 v101, v100
	v_lshl_add_u64 v[118:119], s[10:11], 0, v[118:119]
	s_nop 0
	v_permlane32_swap_b32_e32 v100, v101
	global_store_dwordx4 v[118:119], v[108:111], off
	s_and_saveexec_b64 s[26:27], s[0:1]
	s_cbranch_execz .LBB0_647
	v_lshl_add_u64 v[102:103], v[116:117], 2, s[12:13]
	v_add_f32_e32 v100, v100, v101
	global_atomic_add_f32 v[102:103], v100, off sc1

.LBB0_651:
	v_pk_mul_f32 v[94:95], v[94:95], v[94:95]
	v_pk_mul_f32 v[92:93], v[92:93], v[92:93]
	v_pk_fma_f32 v[98:99], v[98:99], v[98:99], v[94:95]
	v_pk_fma_f32 v[96:97], v[96:97], v[96:97], v[92:93]
	v_cvt_pk_bf16_f32 v92, v88, v89
	v_cvt_pk_bf16_f32 v93, v90, v91
	v_pk_fma_f32 v[90:91], v[90:91], v[90:91], v[98:99]
	v_pk_fma_f32 v[88:89], v[88:89], v[88:89], v[96:97]
	v_cvt_pk_bf16_f32 v94, v84, v85
	v_cvt_pk_bf16_f32 v95, v86, v87
	v_pk_fma_f32 v[86:87], v[86:87], v[86:87], v[90:91]
	v_pk_fma_f32 v[84:85], v[84:85], v[84:85], v[88:89]
	v_lshlrev_b64 v[102:103], 1, v[102:103]
	v_add_f32_e32 v84, v84, v85
	v_add_f32_e32 v85, v86, v87
	v_add_f32_e32 v84, v84, v85
	v_mov_b32_e32 v85, v84
	s_nop 1
	v_permlane16_swap_b32_e32 v84, v85
	v_add_f32_e32 v84, v84, v85
	v_or_b32_e32 v102, 0x100, v102
	v_mov_b32_e32 v85, v84
	v_lshl_add_u64 v[102:103], s[10:11], 0, v[102:103]
	s_nop 0
	v_permlane32_swap_b32_e32 v84, v85
	global_store_dwordx4 v[102:103], v[92:95], off
	s_and_saveexec_b64 s[26:27], s[0:1]
	s_cbranch_execz .LBB0_653
	v_lshl_add_u64 v[86:87], v[100:101], 2, s[12:13]
	v_add_f32_e32 v84, v84, v85
	global_atomic_add_f32 v[86:87], v84, off sc1

.LBB0_657:
	v_pk_mul_f32 v[78:79], v[78:79], v[78:79]
	v_pk_mul_f32 v[76:77], v[76:77], v[76:77]
	v_pk_fma_f32 v[82:83], v[82:83], v[82:83], v[78:79]
	v_pk_fma_f32 v[80:81], v[80:81], v[80:81], v[76:77]
	v_cvt_pk_bf16_f32 v76, v72, v73
	v_cvt_pk_bf16_f32 v77, v74, v75
	v_pk_fma_f32 v[74:75], v[74:75], v[74:75], v[82:83]
	v_pk_fma_f32 v[72:73], v[72:73], v[72:73], v[80:81]
	v_cvt_pk_bf16_f32 v78, v68, v69
	v_cvt_pk_bf16_f32 v79, v70, v71
	v_pk_fma_f32 v[70:71], v[70:71], v[70:71], v[74:75]
	v_pk_fma_f32 v[68:69], v[68:69], v[68:69], v[72:73]
	v_lshlrev_b64 v[86:87], 1, v[86:87]
	v_add_f32_e32 v68, v68, v69
	v_add_f32_e32 v69, v70, v71
	v_add_f32_e32 v68, v68, v69
	v_mov_b32_e32 v69, v68
	s_nop 1
	v_permlane16_swap_b32_e32 v68, v69
	v_add_f32_e32 v68, v68, v69
	v_or_b32_e32 v86, 0x100, v86
	v_mov_b32_e32 v69, v68
	v_lshl_add_u64 v[86:87], s[10:11], 0, v[86:87]
	s_nop 0
	v_permlane32_swap_b32_e32 v68, v69
	global_store_dwordx4 v[86:87], v[76:79], off
	s_and_saveexec_b64 s[26:27], s[0:1]
	s_cbranch_execz .LBB0_659
	v_lshl_add_u64 v[70:71], v[84:85], 2, s[12:13]
	v_add_f32_e32 v68, v68, v69
	global_atomic_add_f32 v[70:71], v68, off sc1

.LBB0_663:
	v_pk_mul_f32 v[62:63], v[62:63], v[62:63]
	v_pk_mul_f32 v[60:61], v[60:61], v[60:61]
	v_pk_fma_f32 v[66:67], v[66:67], v[66:67], v[62:63]
	v_pk_fma_f32 v[64:65], v[64:65], v[64:65], v[60:61]
	v_cvt_pk_bf16_f32 v60, v56, v57
	v_cvt_pk_bf16_f32 v61, v58, v59
	v_pk_fma_f32 v[58:59], v[58:59], v[58:59], v[66:67]
	v_pk_fma_f32 v[56:57], v[56:57], v[56:57], v[64:65]
	v_cvt_pk_bf16_f32 v62, v52, v53
	v_cvt_pk_bf16_f32 v63, v54, v55
	v_pk_fma_f32 v[54:55], v[54:55], v[54:55], v[58:59]
	v_pk_fma_f32 v[52:53], v[52:53], v[52:53], v[56:57]
	v_lshlrev_b64 v[70:71], 1, v[70:71]
	v_add_f32_e32 v52, v52, v53
	v_add_f32_e32 v53, v54, v55
	v_add_f32_e32 v52, v52, v53
	v_mov_b32_e32 v53, v52
	s_nop 1
	v_permlane16_swap_b32_e32 v52, v53
	v_add_f32_e32 v52, v52, v53
	v_or_b32_e32 v70, 0x100, v70
	v_mov_b32_e32 v53, v52
	v_lshl_add_u64 v[70:71], s[10:11], 0, v[70:71]
	s_nop 0
	v_permlane32_swap_b32_e32 v52, v53
	global_store_dwordx4 v[70:71], v[60:63], off
	s_and_saveexec_b64 s[26:27], s[0:1]
	s_cbranch_execz .LBB0_665
	v_lshl_add_u64 v[54:55], v[68:69], 2, s[12:13]
	v_add_f32_e32 v52, v52, v53
	global_atomic_add_f32 v[54:55], v52, off sc1

.LBB0_669:
	v_pk_mul_f32 v[46:47], v[46:47], v[46:47]
	v_pk_mul_f32 v[44:45], v[44:45], v[44:45]
	v_pk_fma_f32 v[50:51], v[50:51], v[50:51], v[46:47]
	v_pk_fma_f32 v[48:49], v[48:49], v[48:49], v[44:45]
	v_cvt_pk_bf16_f32 v44, v40, v41
	v_cvt_pk_bf16_f32 v45, v42, v43
	v_pk_fma_f32 v[42:43], v[42:43], v[42:43], v[50:51]
	v_pk_fma_f32 v[40:41], v[40:41], v[40:41], v[48:49]
	v_cvt_pk_bf16_f32 v46, v36, v37
	v_cvt_pk_bf16_f32 v47, v38, v39
	v_pk_fma_f32 v[38:39], v[38:39], v[38:39], v[42:43]
	v_pk_fma_f32 v[36:37], v[36:37], v[36:37], v[40:41]
	v_lshlrev_b64 v[54:55], 1, v[54:55]
	v_add_f32_e32 v36, v36, v37
	v_add_f32_e32 v37, v38, v39
	v_add_f32_e32 v36, v36, v37
	v_mov_b32_e32 v37, v36
	s_nop 1
	v_permlane16_swap_b32_e32 v36, v37
	v_add_f32_e32 v36, v36, v37
	v_or_b32_e32 v54, 0x100, v54
	v_mov_b32_e32 v37, v36
	v_lshl_add_u64 v[54:55], s[10:11], 0, v[54:55]
	s_nop 0
	v_permlane32_swap_b32_e32 v36, v37
	global_store_dwordx4 v[54:55], v[44:47], off
	s_and_saveexec_b64 s[26:27], s[0:1]
	s_cbranch_execz .LBB0_671
	v_lshl_add_u64 v[38:39], v[52:53], 2, s[12:13]
	v_add_f32_e32 v36, v36, v37
	global_atomic_add_f32 v[38:39], v36, off sc1

.LBB0_675:
	v_pk_mul_f32 v[30:31], v[30:31], v[30:31]
	v_pk_mul_f32 v[28:29], v[28:29], v[28:29]
	v_pk_fma_f32 v[34:35], v[34:35], v[34:35], v[30:31]
	v_pk_fma_f32 v[32:33], v[32:33], v[32:33], v[28:29]
	v_cvt_pk_bf16_f32 v28, v24, v25
	v_cvt_pk_bf16_f32 v29, v26, v27
	v_pk_fma_f32 v[26:27], v[26:27], v[26:27], v[34:35]
	v_pk_fma_f32 v[24:25], v[24:25], v[24:25], v[32:33]
	v_cvt_pk_bf16_f32 v30, v20, v21
	v_cvt_pk_bf16_f32 v31, v22, v23
	v_pk_fma_f32 v[22:23], v[22:23], v[22:23], v[26:27]
	v_pk_fma_f32 v[20:21], v[20:21], v[20:21], v[24:25]
	v_lshlrev_b64 v[38:39], 1, v[38:39]
	v_add_f32_e32 v20, v20, v21
	v_add_f32_e32 v21, v22, v23
	v_add_f32_e32 v20, v20, v21
	v_mov_b32_e32 v21, v20
	s_nop 1
	v_permlane16_swap_b32_e32 v20, v21
	v_add_f32_e32 v20, v20, v21
	v_or_b32_e32 v38, 0x100, v38
	v_mov_b32_e32 v21, v20
	v_lshl_add_u64 v[38:39], s[10:11], 0, v[38:39]
	s_nop 0
	v_permlane32_swap_b32_e32 v20, v21
	global_store_dwordx4 v[38:39], v[28:31], off
	s_and_saveexec_b64 s[26:27], s[0:1]
	s_cbranch_execz .LBB0_677
	v_lshl_add_u64 v[22:23], v[36:37], 2, s[12:13]
	v_add_f32_e32 v20, v20, v21
	global_atomic_add_f32 v[22:23], v20, off sc1

.LBB0_681:
	v_lshlrev_b64 v[2:3], 1, v[2:3]
	v_pk_mul_f32 v[14:15], v[14:15], v[14:15]
	v_pk_mul_f32 v[12:13], v[12:13], v[12:13]
	v_or_b32_e32 v2, 0x100, v2
	v_pk_fma_f32 v[18:19], v[18:19], v[18:19], v[14:15]
	v_pk_fma_f32 v[16:17], v[16:17], v[16:17], v[12:13]
	v_lshl_add_u64 v[2:3], s[10:11], 0, v[2:3]
	v_cvt_pk_bf16_f32 v12, v8, v9
	v_cvt_pk_bf16_f32 v13, v10, v11
	v_cvt_pk_bf16_f32 v14, v4, v5
	v_cvt_pk_bf16_f32 v15, v6, v7
	global_store_dwordx4 v[2:3], v[12:15], off
	v_pk_fma_f32 v[2:3], v[10:11], v[10:11], v[18:19]
	v_pk_fma_f32 v[8:9], v[8:9], v[8:9], v[16:17]
	v_pk_fma_f32 v[2:3], v[6:7], v[6:7], v[2:3]
	v_pk_fma_f32 v[4:5], v[4:5], v[4:5], v[8:9]
	v_add_f32_e32 v2, v2, v3
	v_add_f32_e32 v1, v4, v5
	v_add_f32_e32 v1, v1, v2
	v_mov_b32_e32 v2, v1
	s_nop 1
	v_permlane16_swap_b32_e32 v1, v2
	v_add_f32_e32 v1, v1, v2
	v_mov_b32_e32 v2, v1
	s_nop 1
	v_permlane32_swap_b32_e32 v1, v2
	s_and_saveexec_b64 s[4:5], s[0:1]
	s_cbranch_execz .LBB0_683
	v_lshl_add_u64 v[4:5], v[20:21], 2, s[12:13]
	v_add_f32_e32 v1, v1, v2
	global_atomic_add_f32 v[4:5], v1, off sc1
